# GEMM phase prologue: the second K-tile's first loads (A and wave-0 B pieces) are issued together with the first K-tile's, before the first wait, so the pipeline fill pays one cold latency instead of t
# baseline (speedup 1.0000x reference)
.LBB0_309:
	v_mov_b32_e32 v149, v99
	v_lshl_add_u64 v[2:3], s[68:69], 0, v[148:149]
	v_mov_b32_e32 v153, v99
	v_lshl_add_u64 v[4:5], s[68:69], 0, v[152:153]
	s_add_i32 m0, s0, 0x18000
	v_lshl_add_u64 v[2:3], v[2:3], 0, s[42:43]
	v_lshl_add_u64 v[6:7], s[70:71], 0, v[98:99]
	global_load_lds_dwordx4 v[2:3], off
	v_lshl_add_u64 v[2:3], v[4:5], 0, s[42:43]
	s_add_i32 m0, s0, 0x1a000
	v_mov_b32_e32 v151, v99
	global_load_lds_dwordx4 v[2:3], off
	v_lshl_add_u64 v[2:3], v[6:7], 0, s[42:43]
	s_add_i32 m0, s0, 0x8000
	v_lshl_add_u64 v[8:9], s[70:71], 0, v[150:151]
	global_load_lds_dwordx4 v[2:3], off
	s_add_i32 m0, s0, 0xa000
	s_add_u32 s30, s68, 0x40080
	v_lshl_add_u64 v[2:3], v[8:9], 0, s[42:43]
	s_addc_u32 s31, s69, 0
	global_load_lds_dwordx4 v[2:3], off
	s_add_i32 m0, s0, 0x1c000
	v_lshl_add_u64 v[2:3], s[30:31], 0, v[148:149]
	global_load_lds_dwordx4 v[2:3], off
	v_lshl_add_u64 v[2:3], s[30:31], 0, v[152:153]
	s_add_i32 m0, s0, 0x1e000
	s_mov_b64 s[0:1], 0
	global_load_lds_dwordx4 v[2:3], off
	s_waitcnt vmcnt(8)
	s_barrier
	s_waitcnt vmcnt(6)
	s_barrier

.LBB0_313:
	v_lshl_add_u64 v[2:3], s[70:71], 0, v[98:99]
	v_mov_b32_e32 v151, v99
	v_lshl_add_u64 v[4:5], s[70:71], 0, v[150:151]
	v_lshl_add_u64 v[2:3], v[2:3], 0, s[42:43]
	s_add_i32 m0, s0, 0x8000
	global_load_lds_dwordx4 v[2:3], off
	v_lshl_add_u64 v[2:3], v[4:5], 0, s[42:43]
	s_add_i32 m0, s0, 0xa000
	v_mov_b32_e32 v149, v99
	global_load_lds_dwordx4 v[2:3], off
	s_waitcnt vmcnt(4)
	s_barrier
	s_waitcnt vmcnt(2)
	v_mov_b32_e32 v153, v99
	s_barrier

.LBB0_849:
	v_mov_b32_e32 v205, v99
	v_lshl_add_u64 v[2:3], s[70:71], 0, v[204:205]
	v_mov_b32_e32 v209, v99
	v_lshl_add_u64 v[4:5], s[70:71], 0, v[208:209]
	s_add_i32 m0, s0, 0x18000
	v_lshl_add_u64 v[2:3], v[2:3], 0, s[42:43]
	v_lshl_add_u64 v[6:7], s[68:69], 0, v[98:99]
	global_load_lds_dwordx4 v[2:3], off
	v_lshl_add_u64 v[2:3], v[4:5], 0, s[42:43]
	s_add_i32 m0, s0, 0x1a000
	v_mov_b32_e32 v207, v99
	global_load_lds_dwordx4 v[2:3], off
	v_lshl_add_u64 v[2:3], v[6:7], 0, s[42:43]
	s_add_i32 m0, s0, 0x8000
	v_lshl_add_u64 v[8:9], s[68:69], 0, v[206:207]
	global_load_lds_dwordx4 v[2:3], off
	s_add_i32 m0, s0, 0xa000
	s_add_u32 s4, s70, 0x40080
	v_lshl_add_u64 v[2:3], v[8:9], 0, s[42:43]
	s_addc_u32 s5, s71, 0
	global_load_lds_dwordx4 v[2:3], off
	s_add_i32 m0, s0, 0x1c000
	v_lshl_add_u64 v[2:3], s[4:5], 0, v[204:205]
	global_load_lds_dwordx4 v[2:3], off
	v_lshl_add_u64 v[2:3], s[4:5], 0, v[208:209]
	s_add_i32 m0, s0, 0x1e000
	s_mov_b64 s[0:1], 0
	global_load_lds_dwordx4 v[2:3], off
	s_waitcnt vmcnt(8)
	s_barrier
	s_waitcnt vmcnt(6)
	s_barrier

.LBB0_853:
	v_lshl_add_u64 v[2:3], s[68:69], 0, v[98:99]
	v_mov_b32_e32 v207, v99
	v_lshl_add_u64 v[4:5], s[68:69], 0, v[206:207]
	v_lshl_add_u64 v[2:3], v[2:3], 0, s[42:43]
	s_add_i32 m0, s0, 0x8000
	global_load_lds_dwordx4 v[2:3], off
	v_lshl_add_u64 v[2:3], v[4:5], 0, s[42:43]
	s_add_i32 m0, s0, 0xa000
	v_mov_b32_e32 v205, v99
	global_load_lds_dwordx4 v[2:3], off
	s_waitcnt vmcnt(4)
	s_barrier
	s_waitcnt vmcnt(2)
	s_barrier
	v_mov_b32_e32 v209, v99

.LBB0_893:
	v_mov_b32_e32 v205, v99
	v_lshl_add_u64 v[2:3], s[68:69], 0, v[204:205]
	v_mov_b32_e32 v209, v99
	v_lshl_add_u64 v[4:5], s[68:69], 0, v[208:209]
	s_add_i32 m0, s0, 0x18000
	v_lshl_add_u64 v[2:3], v[2:3], 0, s[42:43]
	v_lshl_add_u64 v[6:7], s[56:57], 0, v[98:99]
	global_load_lds_dwordx4 v[2:3], off
	v_lshl_add_u64 v[2:3], v[4:5], 0, s[42:43]
	s_add_i32 m0, s0, 0x1a000
	v_mov_b32_e32 v207, v99
	global_load_lds_dwordx4 v[2:3], off
	v_lshl_add_u64 v[2:3], v[6:7], 0, s[42:43]
	s_add_i32 m0, s0, 0x8000
	v_lshl_add_u64 v[8:9], s[56:57], 0, v[206:207]
	global_load_lds_dwordx4 v[2:3], off
	s_add_i32 m0, s0, 0xa000
	s_add_u32 s20, s68, 0x40080
	v_lshl_add_u64 v[2:3], v[8:9], 0, s[42:43]
	s_addc_u32 s21, s69, 0
	global_load_lds_dwordx4 v[2:3], off
	s_add_i32 m0, s0, 0x1c000
	v_lshl_add_u64 v[2:3], s[20:21], 0, v[204:205]
	global_load_lds_dwordx4 v[2:3], off
	v_lshl_add_u64 v[2:3], s[20:21], 0, v[208:209]
	s_add_i32 m0, s0, 0x1e000
	s_mov_b64 s[0:1], 0
	global_load_lds_dwordx4 v[2:3], off
	s_waitcnt vmcnt(8)
	s_barrier
	s_waitcnt vmcnt(6)
	s_barrier

.LBB0_897:
	v_lshl_add_u64 v[2:3], s[56:57], 0, v[98:99]
	v_mov_b32_e32 v207, v99
	v_lshl_add_u64 v[4:5], s[56:57], 0, v[206:207]
	v_lshl_add_u64 v[2:3], v[2:3], 0, s[42:43]
	s_add_i32 m0, s0, 0x8000
	global_load_lds_dwordx4 v[2:3], off
	v_lshl_add_u64 v[2:3], v[4:5], 0, s[42:43]
	s_add_i32 m0, s0, 0xa000
	v_mov_b32_e32 v205, v99
	global_load_lds_dwordx4 v[2:3], off
	s_waitcnt vmcnt(4)
	s_barrier
	s_waitcnt vmcnt(2)
	v_mov_b32_e32 v209, v99
	s_barrier

.LBB0_996:
	v_mov_b32_e32 v149, v99
	v_lshl_add_u64 v[2:3], s[56:57], 0, v[148:149]
	v_mov_b32_e32 v153, v99
	v_lshl_add_u64 v[4:5], s[56:57], 0, v[152:153]
	s_add_i32 m0, s0, 0x18000
	v_lshl_add_u64 v[2:3], v[2:3], 0, s[42:43]
	v_lshl_add_u64 v[6:7], s[40:41], 0, v[98:99]
	global_load_lds_dwordx4 v[2:3], off
	v_lshl_add_u64 v[2:3], v[4:5], 0, s[42:43]
	s_add_i32 m0, s0, 0x1a000
	v_mov_b32_e32 v151, v99
	global_load_lds_dwordx4 v[2:3], off
	v_lshl_add_u64 v[2:3], v[6:7], 0, s[42:43]
	s_add_i32 m0, s0, 0x8000
	v_lshl_add_u64 v[8:9], s[40:41], 0, v[150:151]
	global_load_lds_dwordx4 v[2:3], off
	s_add_i32 m0, s0, 0xa000
	s_add_u32 s4, s56, 0x40080
	v_lshl_add_u64 v[2:3], v[8:9], 0, s[42:43]
	s_addc_u32 s5, s57, 0
	global_load_lds_dwordx4 v[2:3], off
	s_add_i32 m0, s0, 0x1c000
	v_lshl_add_u64 v[2:3], s[4:5], 0, v[148:149]
	global_load_lds_dwordx4 v[2:3], off
	v_lshl_add_u64 v[2:3], s[4:5], 0, v[152:153]
	s_add_i32 m0, s0, 0x1e000
	s_mov_b64 s[0:1], 0
	global_load_lds_dwordx4 v[2:3], off
	s_waitcnt vmcnt(8)
	s_barrier
	s_waitcnt vmcnt(6)
	s_barrier

.LBB0_1000:
	v_lshl_add_u64 v[2:3], s[40:41], 0, v[98:99]
	v_mov_b32_e32 v151, v99
	v_lshl_add_u64 v[4:5], s[40:41], 0, v[150:151]
	v_lshl_add_u64 v[2:3], v[2:3], 0, s[42:43]
	s_add_i32 m0, s0, 0x8000
	global_load_lds_dwordx4 v[2:3], off
	v_lshl_add_u64 v[2:3], v[4:5], 0, s[42:43]
	s_add_i32 m0, s0, 0xa000
	v_mov_b32_e32 v149, v99
	global_load_lds_dwordx4 v[2:3], off
	s_waitcnt vmcnt(4)
	s_barrier
	s_waitcnt vmcnt(2)
	v_mov_b32_e32 v153, v99
	s_barrier

.LBB0_1098:
	v_mov_b32_e32 v173, v99
	v_lshl_add_u64 v[2:3], s[78:79], 0, v[172:173]
	v_mov_b32_e32 v177, v99
	v_lshl_add_u64 v[4:5], s[78:79], 0, v[176:177]
	s_add_i32 m0, s10, 0x18000
	v_lshl_add_u64 v[2:3], v[2:3], 0, s[42:43]
	v_lshl_add_u64 v[6:7], s[74:75], 0, v[98:99]
	global_load_lds_dwordx4 v[2:3], off
	v_lshl_add_u64 v[2:3], v[4:5], 0, s[42:43]
	s_add_i32 m0, s10, 0x1a000
	v_mov_b32_e32 v175, v99
	global_load_lds_dwordx4 v[2:3], off
	v_lshl_add_u64 v[2:3], v[6:7], 0, s[42:43]
	s_add_i32 m0, s10, 0x8000
	v_lshl_add_u64 v[8:9], s[74:75], 0, v[174:175]
	global_load_lds_dwordx4 v[2:3], off
	s_add_i32 m0, s10, 0xa000
	s_add_u32 s4, s78, 0x100080
	v_lshl_add_u64 v[2:3], v[8:9], 0, s[42:43]
	s_addc_u32 s5, s79, 0
	global_load_lds_dwordx4 v[2:3], off
	s_add_i32 m0, s10, 0x1c000
	v_lshl_add_u64 v[2:3], s[4:5], 0, v[172:173]
	global_load_lds_dwordx4 v[2:3], off
	v_lshl_add_u64 v[2:3], s[4:5], 0, v[176:177]
	s_add_i32 m0, s10, 0x1e000
	s_mov_b64 s[10:11], 0
	global_load_lds_dwordx4 v[2:3], off
	s_waitcnt vmcnt(8)
	s_barrier
	s_waitcnt vmcnt(6)
	s_barrier

.LBB0_1102:
	v_lshl_add_u64 v[2:3], s[74:75], 0, v[98:99]
	v_mov_b32_e32 v175, v99
	v_lshl_add_u64 v[4:5], s[74:75], 0, v[174:175]
	v_lshl_add_u64 v[2:3], v[2:3], 0, s[42:43]
	s_add_i32 m0, s10, 0x8000
	global_load_lds_dwordx4 v[2:3], off
	v_lshl_add_u64 v[2:3], v[4:5], 0, s[42:43]
	s_add_i32 m0, s10, 0xa000
	v_mov_b32_e32 v173, v99
	global_load_lds_dwordx4 v[2:3], off
	s_waitcnt vmcnt(4)
	s_barrier
	s_waitcnt vmcnt(2)
	v_mov_b32_e32 v177, v99
	s_barrier

.LBB0_1154:
	v_mov_b32_e32 v205, v99
	v_lshl_add_u64 v[2:3], s[74:75], 0, v[204:205]
	v_mov_b32_e32 v209, v99
	v_lshl_add_u64 v[4:5], s[74:75], 0, v[208:209]
	s_add_i32 m0, s10, 0x18000
	v_lshl_add_u64 v[2:3], v[2:3], 0, s[42:43]
	v_lshl_add_u64 v[6:7], s[70:71], 0, v[98:99]
	global_load_lds_dwordx4 v[2:3], off
	v_lshl_add_u64 v[2:3], v[4:5], 0, s[42:43]
	s_add_i32 m0, s10, 0x1a000
	v_mov_b32_e32 v207, v99
	global_load_lds_dwordx4 v[2:3], off
	v_lshl_add_u64 v[2:3], v[6:7], 0, s[42:43]
	s_add_i32 m0, s10, 0x8000
	v_lshl_add_u64 v[8:9], s[70:71], 0, v[206:207]
	global_load_lds_dwordx4 v[2:3], off
	s_add_i32 m0, s10, 0xa000
	s_add_u32 s4, s74, 0x100080
	v_lshl_add_u64 v[2:3], v[8:9], 0, s[42:43]
	s_addc_u32 s5, s75, 0
	global_load_lds_dwordx4 v[2:3], off
	s_add_i32 m0, s10, 0x1c000
	v_lshl_add_u64 v[2:3], s[4:5], 0, v[204:205]
	global_load_lds_dwordx4 v[2:3], off
	v_lshl_add_u64 v[2:3], s[4:5], 0, v[208:209]
	s_add_i32 m0, s10, 0x1e000
	s_mov_b64 s[10:11], 0
	global_load_lds_dwordx4 v[2:3], off
	s_waitcnt vmcnt(8)
	s_barrier
	s_waitcnt vmcnt(6)
	s_barrier

.LBB0_1158:
	v_lshl_add_u64 v[2:3], s[70:71], 0, v[98:99]
	v_mov_b32_e32 v207, v99
	v_lshl_add_u64 v[4:5], s[70:71], 0, v[206:207]
	v_lshl_add_u64 v[2:3], v[2:3], 0, s[42:43]
	s_add_i32 m0, s10, 0x8000
	global_load_lds_dwordx4 v[2:3], off
	v_lshl_add_u64 v[2:3], v[4:5], 0, s[42:43]
	s_add_i32 m0, s10, 0xa000
	v_mov_b32_e32 v205, v99
	global_load_lds_dwordx4 v[2:3], off
	s_waitcnt vmcnt(4)
	s_barrier
	s_waitcnt vmcnt(2)
	v_mov_b32_e32 v209, v99
	s_barrier
